# attn inst1: V-fragment ds_reads hoisted half a group ahead (double-buffered in free VGPRs), lgkmcnt recounted
# baseline (speedup 1.0000x reference)
.LBB0_863:
	ds_read_b64_tr_b16 v[148:149], v215 offset:17408
	ds_read_b64_tr_b16 v[152:153], v215 offset:17440
	ds_read_b64_tr_b16 v[156:157], v215 offset:17472
	ds_read_b64_tr_b16 v[160:161], v215 offset:17504
	ds_read_b64_tr_b16 v[150:151], v215 offset:22016
	ds_read_b64_tr_b16 v[154:155], v215 offset:22048
	ds_read_b64_tr_b16 v[158:159], v215 offset:22080
	ds_read_b64_tr_b16 v[162:163], v215 offset:22112
	v_exp_f32_e32 v2, v144
	s_waitcnt lgkmcnt(3)
	v_mfma_f32_16x16x32_bf16 v[164:167], v[36:39], v[148:151], v[128:131]
	v_exp_f32_e32 v222, v145
	v_mfma_f32_16x16x32_bf16 v[148:151], v[60:63], v[148:151], v[120:123]
	ds_read_b64_tr_b16 v[238:239], v215 offset:17536
	ds_read_b64_tr_b16 v[242:243], v215 offset:17568
	ds_read_b64_tr_b16 v[246:247], v215 offset:17600
	ds_read_b64_tr_b16 v[250:251], v215 offset:17632
	ds_read_b64_tr_b16 v[240:241], v215 offset:22144
	ds_read_b64_tr_b16 v[244:245], v215 offset:22176
	ds_read_b64_tr_b16 v[248:249], v215 offset:22208
	ds_read_b64_tr_b16 v[252:253], v215 offset:22240
	v_exp_f32_e32 v224, v146
	s_waitcnt lgkmcnt(10)
	v_mfma_f32_16x16x32_bf16 v[124:127], v[36:39], v[152:155], v[124:127]
	v_exp_f32_e32 v122, v147
	v_mfma_f32_16x16x32_bf16 v[152:155], v[60:63], v[152:155], v[108:111]
	v_exp_f32_e32 v226, v44
	s_waitcnt lgkmcnt(9)
	v_mfma_f32_16x16x32_bf16 v[116:119], v[36:39], v[156:159], v[116:119]
	v_exp_f32_e32 v110, v45
	v_mfma_f32_16x16x32_bf16 v[168:171], v[60:63], v[156:159], v[100:103]
	v_exp_f32_e32 v228, v46
	s_waitcnt lgkmcnt(8)
	v_mfma_f32_16x16x32_bf16 v[104:107], v[36:39], v[160:163], v[104:107]
	v_exp_f32_e32 v100, v47
	v_mfma_f32_16x16x32_bf16 v[160:163], v[60:63], v[160:163], v[96:99]
	v_cvt_pk_bf16_f32 v44, v2, v222
	v_cvt_pk_bf16_f32 v45, v224, v122
	v_cvt_pk_bf16_f32 v46, v226, v110
	v_cvt_pk_bf16_f32 v47, v228, v100
	v_exp_f32_e32 v96, v140
	s_waitcnt lgkmcnt(3)
	v_mfma_f32_16x16x32_bf16 v[180:183], v[36:39], v[238:241], v[88:91]
	v_exp_f32_e32 v230, v141
	v_mfma_f32_16x16x32_bf16 v[184:187], v[60:63], v[238:241], v[76:79]
	v_exp_f32_e32 v232, v142
	s_waitcnt lgkmcnt(2)
	v_mfma_f32_16x16x32_bf16 v[80:83], v[36:39], v[242:245], v[80:83]
	v_exp_f32_e32 v78, v143
	v_mfma_f32_16x16x32_bf16 v[188:191], v[60:63], v[242:245], v[64:67]
	ds_read_b64_tr_b16 v[140:141], v215 offset:26624
	ds_read_b64_tr_b16 v[156:157], v215 offset:26656
	ds_read_b64_tr_b16 v[172:173], v215 offset:26688
	ds_read_b64_tr_b16 v[176:177], v215 offset:26720
	ds_read_b64_tr_b16 v[142:143], v215 offset:31232
	ds_read_b64_tr_b16 v[158:159], v215 offset:31264
	ds_read_b64_tr_b16 v[174:175], v215 offset:31296
	ds_read_b64_tr_b16 v[178:179], v215 offset:31328
	v_exp_f32_e32 v234, v72
	s_waitcnt lgkmcnt(9)
	v_mfma_f32_16x16x32_bf16 v[68:71], v[36:39], v[246:249], v[68:71]
	v_exp_f32_e32 v66, v73
	v_mfma_f32_16x16x32_bf16 v[192:195], v[60:63], v[246:249], v[52:55]
	v_exp_f32_e32 v236, v74
	s_waitcnt lgkmcnt(8)
	v_mfma_f32_16x16x32_bf16 v[56:59], v[36:39], v[250:253], v[56:59]
	v_exp_f32_e32 v54, v75
	v_mfma_f32_16x16x32_bf16 v[48:51], v[60:63], v[250:253], v[48:51]
	v_cvt_pk_bf16_f32 v72, v96, v230
	v_cvt_pk_bf16_f32 v73, v232, v78
	v_cvt_pk_bf16_f32 v74, v234, v66
	v_cvt_pk_bf16_f32 v75, v236, v54
	v_exp_f32_e32 v3, v136
	s_waitcnt lgkmcnt(3)
	v_mfma_f32_16x16x32_bf16 v[144:147], v[40:43], v[140:143], v[164:167]
	v_exp_f32_e32 v223, v137
	v_mfma_f32_16x16x32_bf16 v[140:143], v[84:87], v[140:143], v[148:151]
	ds_read_b64_tr_b16 v[238:239], v215 offset:26752
	ds_read_b64_tr_b16 v[242:243], v215 offset:26784
	ds_read_b64_tr_b16 v[246:247], v215 offset:26816
	ds_read_b64_tr_b16 v[250:251], v215 offset:26848
	ds_read_b64_tr_b16 v[240:241], v215 offset:31360
	ds_read_b64_tr_b16 v[244:245], v215 offset:31392
	ds_read_b64_tr_b16 v[248:249], v215 offset:31424
	ds_read_b64_tr_b16 v[252:253], v215 offset:31456
	v_exp_f32_e32 v225, v138
	s_waitcnt lgkmcnt(10)
	v_mfma_f32_16x16x32_bf16 v[148:151], v[40:43], v[156:159], v[124:127]
	v_exp_f32_e32 v123, v139
	v_mfma_f32_16x16x32_bf16 v[136:139], v[84:87], v[156:159], v[152:155]
	v_exp_f32_e32 v227, v92
	s_waitcnt lgkmcnt(9)
	v_mfma_f32_16x16x32_bf16 v[156:159], v[40:43], v[172:175], v[116:119]
	v_exp_f32_e32 v111, v93
	v_mfma_f32_16x16x32_bf16 v[152:155], v[84:87], v[172:175], v[168:171]
	v_exp_f32_e32 v229, v94
	s_waitcnt lgkmcnt(8)
	v_mfma_f32_16x16x32_bf16 v[164:167], v[40:43], v[176:179], v[104:107]
	v_exp_f32_e32 v101, v95
	v_mfma_f32_16x16x32_bf16 v[160:163], v[84:87], v[176:179], v[160:163]
	s_nop 0
	v_cvt_pk_bf16_f32 v92, v3, v223
	v_cvt_pk_bf16_f32 v93, v225, v123
	v_cvt_pk_bf16_f32 v94, v227, v111
	v_cvt_pk_bf16_f32 v95, v229, v101
	v_exp_f32_e32 v97, v132
	s_waitcnt lgkmcnt(3)
	v_mfma_f32_16x16x32_bf16 v[172:175], v[40:43], v[238:241], v[180:183]
	v_exp_f32_e32 v231, v133
	v_mfma_f32_16x16x32_bf16 v[168:171], v[84:87], v[238:241], v[184:187]
	v_exp_f32_e32 v233, v134
	s_waitcnt lgkmcnt(2)
	v_mfma_f32_16x16x32_bf16 v[176:179], v[40:43], v[242:245], v[80:83]
	v_exp_f32_e32 v79, v135
	v_mfma_f32_16x16x32_bf16 v[132:135], v[84:87], v[242:245], v[188:191]
	v_exp_f32_e32 v235, v112
	s_waitcnt lgkmcnt(1)
	v_mfma_f32_16x16x32_bf16 v[184:187], v[40:43], v[246:249], v[68:71]
	v_exp_f32_e32 v67, v113
	v_mfma_f32_16x16x32_bf16 v[180:183], v[84:87], v[246:249], v[192:195]
	v_exp_f32_e32 v237, v114
	s_waitcnt lgkmcnt(0)
	v_mfma_f32_16x16x32_bf16 v[192:195], v[40:43], v[250:253], v[56:59]
	v_exp_f32_e32 v55, v115
	v_mfma_f32_16x16x32_bf16 v[188:191], v[84:87], v[250:253], v[48:51]
	v_cvt_pk_bf16_f32 v112, v97, v231
	v_cvt_pk_bf16_f32 v113, v233, v79
	v_cvt_pk_bf16_f32 v114, v235, v67
	v_cvt_pk_bf16_f32 v115, v237, v55
	s_andn2_b64 vcc, exec, s[0:1]
	s_cbranch_vccnz .LBB0_865
	v_mov_b32_e32 v0, v210
	s_nop 0
	v_lshlrev_b32_e32 v0, 2, v0
	v_and_b32_e32 v0, 60, v0
	v_and_or_b32 v0, v212, 64, v0
	v_lshlrev_b32_e32 v0, 2, v0
	ds_bpermute_b32 v48, v0, v200
	ds_bpermute_b32 v50, v0, v200 offset:8
	ds_bpermute_b32 v51, v0, v200 offset:12
	ds_bpermute_b32 v49, v0, v200 offset:4
	ds_bpermute_b32 v56, v0, v201
	ds_bpermute_b32 v58, v0, v201 offset:8
	ds_bpermute_b32 v59, v0, v201 offset:12
	ds_bpermute_b32 v57, v0, v201 offset:4
	s_waitcnt lgkmcnt(5)
	v_pk_mul_f32 v[146:147], v[146:147], v[50:51]
	s_waitcnt lgkmcnt(4)
	v_pk_mul_f32 v[144:145], v[144:145], v[48:49]
	v_pk_mul_f32 v[150:151], v[150:151], v[50:51]
	v_pk_mul_f32 v[148:149], v[148:149], v[48:49]
	v_pk_mul_f32 v[158:159], v[158:159], v[50:51]
	v_pk_mul_f32 v[156:157], v[156:157], v[48:49]
	v_pk_mul_f32 v[166:167], v[166:167], v[50:51]
	v_pk_mul_f32 v[164:165], v[164:165], v[48:49]
	v_pk_mul_f32 v[174:175], v[174:175], v[50:51]
	v_pk_mul_f32 v[172:173], v[172:173], v[48:49]
	v_pk_mul_f32 v[178:179], v[178:179], v[50:51]
	v_pk_mul_f32 v[176:177], v[176:177], v[48:49]
	v_pk_mul_f32 v[186:187], v[186:187], v[50:51]
	v_pk_mul_f32 v[184:185], v[184:185], v[48:49]
	v_pk_mul_f32 v[194:195], v[194:195], v[50:51]
	v_pk_mul_f32 v[192:193], v[192:193], v[48:49]
	s_waitcnt lgkmcnt(1)
	v_pk_mul_f32 v[142:143], v[142:143], v[58:59]
	s_waitcnt lgkmcnt(0)
	v_pk_mul_f32 v[140:141], v[140:141], v[56:57]
	v_pk_mul_f32 v[138:139], v[138:139], v[58:59]
	v_pk_mul_f32 v[136:137], v[136:137], v[56:57]
	v_pk_mul_f32 v[154:155], v[154:155], v[58:59]
	v_pk_mul_f32 v[152:153], v[152:153], v[56:57]
	v_pk_mul_f32 v[162:163], v[162:163], v[58:59]
	v_pk_mul_f32 v[160:161], v[160:161], v[56:57]
	v_pk_mul_f32 v[170:171], v[170:171], v[58:59]
	v_pk_mul_f32 v[168:169], v[168:169], v[56:57]
	v_pk_mul_f32 v[134:135], v[134:135], v[58:59]
	v_pk_mul_f32 v[132:133], v[132:133], v[56:57]
	v_pk_mul_f32 v[182:183], v[182:183], v[58:59]
	v_pk_mul_f32 v[180:181], v[180:181], v[56:57]
	v_pk_mul_f32 v[190:191], v[190:191], v[58:59]
	v_pk_mul_f32 v[188:189], v[188:189], v[56:57]

.LBB0_879:
	ds_read_b64_tr_b16 v[124:125], v215 offset:53248
	ds_read_b64_tr_b16 v[100:101], v215 offset:53280
	ds_read_b64_tr_b16 v[116:117], v215 offset:53312
	ds_read_b64_tr_b16 v[96:97], v215 offset:53344
	ds_read_b64_tr_b16 v[126:127], v215 offset:57856
	ds_read_b64_tr_b16 v[102:103], v215 offset:57888
	ds_read_b64_tr_b16 v[118:119], v215 offset:57920
	ds_read_b64_tr_b16 v[98:99], v215 offset:57952
	v_exp_f32_e32 v2, v128
	s_waitcnt lgkmcnt(3)
	v_mfma_f32_16x16x32_bf16 v[104:107], v[44:47], v[124:127], v[144:147]
	v_exp_f32_e32 v222, v129
	v_mfma_f32_16x16x32_bf16 v[124:127], v[92:95], v[124:127], v[140:143]
	ds_read_b64_tr_b16 v[238:239], v215 offset:53376
	ds_read_b64_tr_b16 v[242:243], v215 offset:53408
	ds_read_b64_tr_b16 v[246:247], v215 offset:53440
	ds_read_b64_tr_b16 v[250:251], v215 offset:53472
	ds_read_b64_tr_b16 v[240:241], v215 offset:57984
	ds_read_b64_tr_b16 v[244:245], v215 offset:58016
	ds_read_b64_tr_b16 v[248:249], v215 offset:58048
	ds_read_b64_tr_b16 v[252:253], v215 offset:58080
	v_exp_f32_e32 v224, v130
	s_waitcnt lgkmcnt(10)
	v_mfma_f32_16x16x32_bf16 v[148:151], v[44:47], v[100:103], v[148:151]
	v_exp_f32_e32 v142, v131
	v_mfma_f32_16x16x32_bf16 v[100:103], v[92:95], v[100:103], v[136:139]
	v_exp_f32_e32 v226, v36
	s_waitcnt lgkmcnt(9)
	v_mfma_f32_16x16x32_bf16 v[156:159], v[44:47], v[116:119], v[156:159]
	v_exp_f32_e32 v138, v37
	v_mfma_f32_16x16x32_bf16 v[76:79], v[92:95], v[116:119], v[152:155]
	v_exp_f32_e32 v228, v38
	s_waitcnt lgkmcnt(8)
	v_mfma_f32_16x16x32_bf16 v[164:167], v[44:47], v[96:99], v[164:167]
	v_exp_f32_e32 v154, v39
	v_mfma_f32_16x16x32_bf16 v[96:99], v[92:95], v[96:99], v[160:163]
	v_cvt_pk_bf16_f32 v36, v2, v222
	v_cvt_pk_bf16_f32 v37, v224, v142
	v_cvt_pk_bf16_f32 v38, v226, v138
	v_cvt_pk_bf16_f32 v39, v228, v154
	v_exp_f32_e32 v160, v120
	s_waitcnt lgkmcnt(3)
	v_mfma_f32_16x16x32_bf16 v[52:55], v[44:47], v[238:241], v[172:175]
	v_exp_f32_e32 v230, v121
	v_mfma_f32_16x16x32_bf16 v[68:71], v[92:95], v[238:241], v[168:171]
	v_exp_f32_e32 v232, v122
	s_waitcnt lgkmcnt(2)
	v_mfma_f32_16x16x32_bf16 v[176:179], v[44:47], v[242:245], v[176:179]
	v_exp_f32_e32 v170, v123
	v_mfma_f32_16x16x32_bf16 v[48:51], v[92:95], v[242:245], v[132:135]
	ds_read_b64_tr_b16 v[120:121], v215 offset:62464
	ds_read_b64_tr_b16 v[116:117], v215 offset:62496
	ds_read_b64_tr_b16 v[88:89], v215 offset:62528
	ds_read_b64_tr_b16 v[80:81], v215 offset:62560
	ds_read_b64_tr_b16 v[122:123], v216 offset:13824
	ds_read_b64_tr_b16 v[118:119], v216 offset:13856
	ds_read_b64_tr_b16 v[90:91], v216 offset:13888
	ds_read_b64_tr_b16 v[82:83], v216 offset:13920
	v_exp_f32_e32 v234, v40
	s_waitcnt lgkmcnt(9)
	v_mfma_f32_16x16x32_bf16 v[184:187], v[44:47], v[246:249], v[184:187]
	v_exp_f32_e32 v134, v41
	v_mfma_f32_16x16x32_bf16 v[56:59], v[92:95], v[246:249], v[180:183]
	v_exp_f32_e32 v236, v42
	s_waitcnt lgkmcnt(8)
	v_mfma_f32_16x16x32_bf16 v[192:195], v[44:47], v[250:253], v[192:195]
	v_exp_f32_e32 v182, v43
	v_mfma_f32_16x16x32_bf16 v[188:191], v[92:95], v[250:253], v[188:191]
	v_cvt_pk_bf16_f32 v40, v160, v230
	v_cvt_pk_bf16_f32 v41, v232, v170
	v_cvt_pk_bf16_f32 v42, v234, v134
	v_cvt_pk_bf16_f32 v43, v236, v182
	v_exp_f32_e32 v3, v108
	s_waitcnt lgkmcnt(3)
	v_mfma_f32_16x16x32_bf16 v[128:131], v[72:75], v[120:123], v[104:107]
	v_exp_f32_e32 v223, v109
	v_mfma_f32_16x16x32_bf16 v[120:123], v[112:115], v[120:123], v[124:127]
	ds_read_b64_tr_b16 v[238:239], v215 offset:62592
	ds_read_b64_tr_b16 v[242:243], v215 offset:62624
	ds_read_b64_tr_b16 v[246:247], v215 offset:62656
	ds_read_b64_tr_b16 v[250:251], v215 offset:62688
	ds_read_b64_tr_b16 v[240:241], v216 offset:13952
	ds_read_b64_tr_b16 v[244:245], v216 offset:13984
	ds_read_b64_tr_b16 v[248:249], v216 offset:14016
	ds_read_b64_tr_b16 v[252:253], v216 offset:14048
	v_exp_f32_e32 v225, v110
	s_waitcnt lgkmcnt(10)
	v_mfma_f32_16x16x32_bf16 v[124:127], v[72:75], v[116:119], v[148:151]
	v_exp_f32_e32 v143, v111
	v_mfma_f32_16x16x32_bf16 v[108:111], v[112:115], v[116:119], v[100:103]
	v_exp_f32_e32 v227, v60
	s_waitcnt lgkmcnt(9)
	v_mfma_f32_16x16x32_bf16 v[116:119], v[72:75], v[88:91], v[156:159]
	v_exp_f32_e32 v139, v61
	v_mfma_f32_16x16x32_bf16 v[100:103], v[112:115], v[88:91], v[76:79]
	v_exp_f32_e32 v229, v62
	s_waitcnt lgkmcnt(8)
	v_mfma_f32_16x16x32_bf16 v[104:107], v[72:75], v[80:83], v[164:167]
	v_exp_f32_e32 v155, v63
	v_mfma_f32_16x16x32_bf16 v[96:99], v[112:115], v[80:83], v[96:99]
	s_nop 0
	v_cvt_pk_bf16_f32 v60, v3, v223
	v_cvt_pk_bf16_f32 v61, v225, v143
	v_cvt_pk_bf16_f32 v62, v227, v139
	v_cvt_pk_bf16_f32 v63, v229, v155
	v_exp_f32_e32 v161, v64
	s_waitcnt lgkmcnt(3)
	v_mfma_f32_16x16x32_bf16 v[88:91], v[72:75], v[238:241], v[52:55]
	v_exp_f32_e32 v231, v65
	v_mfma_f32_16x16x32_bf16 v[76:79], v[112:115], v[238:241], v[68:71]
	v_exp_f32_e32 v233, v66
	s_waitcnt lgkmcnt(2)
	v_mfma_f32_16x16x32_bf16 v[80:83], v[72:75], v[242:245], v[176:179]
	v_exp_f32_e32 v171, v67
	v_mfma_f32_16x16x32_bf16 v[64:67], v[112:115], v[242:245], v[48:51]
	v_exp_f32_e32 v235, v84
	s_waitcnt lgkmcnt(1)
	v_mfma_f32_16x16x32_bf16 v[68:71], v[72:75], v[246:249], v[184:187]
	v_exp_f32_e32 v135, v85
	v_mfma_f32_16x16x32_bf16 v[52:55], v[112:115], v[246:249], v[56:59]
	v_exp_f32_e32 v237, v86
	s_waitcnt lgkmcnt(0)
	v_mfma_f32_16x16x32_bf16 v[56:59], v[72:75], v[250:253], v[192:195]
	v_exp_f32_e32 v183, v87
	v_mfma_f32_16x16x32_bf16 v[48:51], v[112:115], v[250:253], v[188:191]
	v_cvt_pk_bf16_f32 v84, v161, v231
	v_cvt_pk_bf16_f32 v85, v233, v171
	v_cvt_pk_bf16_f32 v86, v235, v135
	v_cvt_pk_bf16_f32 v87, v237, v183
	s_andn2_b64 vcc, exec, s[2:3]
	s_cbranch_vccnz .LBB0_881
	v_mov_b32_e32 v0, v210
	s_nop 0
	v_lshlrev_b32_e32 v0, 2, v0
	v_and_b32_e32 v0, 60, v0
	v_and_or_b32 v0, v212, 64, v0
	v_lshlrev_b32_e32 v0, 2, v0
	ds_bpermute_b32 v188, v0, v200
	ds_bpermute_b32 v190, v0, v200 offset:8
	ds_bpermute_b32 v191, v0, v200 offset:12
	ds_bpermute_b32 v189, v0, v200 offset:4
	ds_bpermute_b32 v192, v0, v201
	ds_bpermute_b32 v194, v0, v201 offset:8
	ds_bpermute_b32 v195, v0, v201 offset:12
	ds_bpermute_b32 v193, v0, v201 offset:4
	s_waitcnt lgkmcnt(5)
	v_pk_mul_f32 v[130:131], v[130:131], v[190:191]
	s_waitcnt lgkmcnt(4)
	v_pk_mul_f32 v[128:129], v[128:129], v[188:189]
	v_pk_mul_f32 v[126:127], v[126:127], v[190:191]
	v_pk_mul_f32 v[124:125], v[124:125], v[188:189]
	v_pk_mul_f32 v[118:119], v[118:119], v[190:191]
	v_pk_mul_f32 v[116:117], v[116:117], v[188:189]
	v_pk_mul_f32 v[106:107], v[106:107], v[190:191]
	v_pk_mul_f32 v[104:105], v[104:105], v[188:189]
	v_pk_mul_f32 v[90:91], v[90:91], v[190:191]
	v_pk_mul_f32 v[88:89], v[88:89], v[188:189]
	v_pk_mul_f32 v[82:83], v[82:83], v[190:191]
	v_pk_mul_f32 v[80:81], v[80:81], v[188:189]
	v_pk_mul_f32 v[70:71], v[70:71], v[190:191]
	v_pk_mul_f32 v[68:69], v[68:69], v[188:189]
	v_pk_mul_f32 v[58:59], v[58:59], v[190:191]
	v_pk_mul_f32 v[56:57], v[56:57], v[188:189]
	s_waitcnt lgkmcnt(1)
	v_pk_mul_f32 v[122:123], v[122:123], v[194:195]
	s_waitcnt lgkmcnt(0)
	v_pk_mul_f32 v[120:121], v[120:121], v[192:193]
	v_pk_mul_f32 v[110:111], v[110:111], v[194:195]
	v_pk_mul_f32 v[108:109], v[108:109], v[192:193]
	v_pk_mul_f32 v[102:103], v[102:103], v[194:195]
	v_pk_mul_f32 v[100:101], v[100:101], v[192:193]
	v_pk_mul_f32 v[98:99], v[98:99], v[194:195]
	v_pk_mul_f32 v[96:97], v[96:97], v[192:193]
	v_pk_mul_f32 v[78:79], v[78:79], v[194:195]
	v_pk_mul_f32 v[76:77], v[76:77], v[192:193]
	v_pk_mul_f32 v[66:67], v[66:67], v[194:195]
	v_pk_mul_f32 v[64:65], v[64:65], v[192:193]
	v_pk_mul_f32 v[54:55], v[54:55], v[194:195]
	v_pk_mul_f32 v[52:53], v[52:53], v[192:193]
	v_pk_mul_f32 v[50:51], v[50:51], v[194:195]
	v_pk_mul_f32 v[48:49], v[48:49], v[192:193]
